# sample-row GEMM K loops fully unrolled with 11-12 k-steps of loads in flight; their epilogue loads batched
# speedup vs baseline: 1.0055x; 1.0055x over previous
; template <int MODE>
; __device__ __forceinline__ void sample_gemm(const Params& p, int l, const int tid) {
;     ...
;     for (int sl = blockIdx.x; sl < 128; sl += gridDim.x) {
;         const int n0 = sl * 16;
;         const bf16_t* a0 = A + (size_t)(wid * 32 + r16) * 2048 + quad * 8; const bf16_t* a1 = a0 + 16 * 2048; const bf16_t* bp = Bt + (size_t)(n0 + r16) * 2048 + quad * 8;
;         f32x4 c[2][2];
; #pragma unroll
;         for (int i = 0; i < 2; ++i)
; #pragma unroll
;             for (int j = 0; j < 2; ++j) c[i][j] = (f32x4){0.f, 0.f, 0.f, 0.f};
; #pragma unroll
;         for (int hh = 0; hh < 2; ++hh) {
; #pragma unroll 8
;             for (int k = hh * 1024; k < hh * 1024 + 1024; k += 32) {
;                 const bf16x8 fa0 = *(const bf16x8*)(a0 + k), fa1 = *(const bf16x8*)(a1 + k), fb = *(const bf16x8*)(bp + k);
;                 const int ci = (MODE == 2) ? hh : 0;
;                 c[ci][0] = __builtin_amdgcn_mfma_f32_16x16x32_bf16(fa0, fb, c[ci][0], 0, 0, 0);
;                 c[ci][1] = __builtin_amdgcn_mfma_f32_16x16x32_bf16(fa1, fb, c[ci][1], 0, 0, 0);
;             }
.LBB0_17:
	v_readlane_b32 s12, v248, 4
	v_readlane_b32 s13, v248, 5
	s_load_dwordx2 s[12:13], s[12:13], 0xb8
	v_ashrrev_i32_e32 v35, 31, v34
	v_lshlrev_b64 v[0:1], 12, v[34:35]
	v_mov_b32_e32 v4, 0
	s_movk_i32 s11, 0xffe0
	s_waitcnt lgkmcnt(0)
	v_lshl_add_u64 v[36:37], s[12:13], 0, v[0:1]
	v_mov_b64_e32 v[8:9], v[36:37]
	v_mov_b64_e32 v[10:11], v[32:33]
	v_mov_b32_e32 v5, v4
	v_mov_b32_e32 v6, v4
	v_mov_b32_e32 v7, v4
	v_mov_b32_e32 v0, v4
	v_mov_b32_e32 v1, v4
	v_mov_b32_e32 v2, v4
	v_mov_b32_e32 v3, v4
	v_lshl_add_u64 v[38:39], v[32:33], 0, v[136:137]
	v_lshl_add_u64 v[42:43], v[36:37], 0, v[136:137]
	s_mov_b64 s[12:13], 0xc100000
	v_lshl_add_u64 v[38:39], v[38:39], 0, s[12:13]
	s_mov_b64 s[12:13], 0x10000
	v_lshl_add_u64 v[40:41], v[38:39], 0, s[12:13]
	s_mov_b64 s[12:13], 0x3100000
	v_lshl_add_u64 v[42:43], v[42:43], 0, s[12:13]
	v_mov_b32_e32 v8, 0
	v_mov_b32_e32 v9, 0
	v_mov_b32_e32 v10, 0
	v_mov_b32_e32 v11, 0
	v_mov_b32_e32 v12, 0
	v_mov_b32_e32 v13, 0
	v_mov_b32_e32 v14, 0
	v_mov_b32_e32 v15, 0
	global_load_dwordx4 v[48:51], v[38:39], off
	global_load_dwordx4 v[52:55], v[40:41], off
	global_load_dwordx4 v[56:59], v[42:43], off
	global_load_dwordx4 v[60:63], v[38:39], off offset:64
	global_load_dwordx4 v[64:67], v[40:41], off offset:64
	global_load_dwordx4 v[68:71], v[42:43], off offset:64
	global_load_dwordx4 v[72:75], v[38:39], off offset:128
	global_load_dwordx4 v[76:79], v[40:41], off offset:128
	global_load_dwordx4 v[80:83], v[42:43], off offset:128
	global_load_dwordx4 v[84:87], v[38:39], off offset:192
	global_load_dwordx4 v[88:91], v[40:41], off offset:192
	global_load_dwordx4 v[92:95], v[42:43], off offset:192
	global_load_dwordx4 v[96:99], v[38:39], off offset:256
	global_load_dwordx4 v[100:103], v[40:41], off offset:256
	global_load_dwordx4 v[104:107], v[42:43], off offset:256
	global_load_dwordx4 v[108:111], v[38:39], off offset:320
	global_load_dwordx4 v[112:115], v[40:41], off offset:320
	global_load_dwordx4 v[116:119], v[42:43], off offset:320
	global_load_dwordx4 v[120:123], v[38:39], off offset:384
	global_load_dwordx4 v[124:127], v[40:41], off offset:384
	global_load_dwordx4 v[128:131], v[42:43], off offset:384
	global_load_dwordx4 v[140:143], v[38:39], off offset:448
	global_load_dwordx4 v[144:147], v[40:41], off offset:448
	global_load_dwordx4 v[148:151], v[42:43], off offset:448
	global_load_dwordx4 v[152:155], v[38:39], off offset:512
	global_load_dwordx4 v[156:159], v[40:41], off offset:512
	global_load_dwordx4 v[160:163], v[42:43], off offset:512
	global_load_dwordx4 v[164:167], v[38:39], off offset:576
	global_load_dwordx4 v[168:171], v[40:41], off offset:576
	global_load_dwordx4 v[172:175], v[42:43], off offset:576
	global_load_dwordx4 v[192:195], v[38:39], off offset:640
	global_load_dwordx4 v[196:199], v[40:41], off offset:640
	global_load_dwordx4 v[200:203], v[42:43], off offset:640
	global_load_dwordx4 v[216:219], v[38:39], off offset:704
	global_load_dwordx4 v[220:223], v[40:41], off offset:704
	global_load_dwordx4 v[224:227], v[42:43], off offset:704
	s_waitcnt vmcnt(33)
	v_mfma_f32_16x16x32_bf16 v[4:7], v[48:51], v[56:59], v[4:7]
	v_mfma_f32_16x16x32_bf16 v[0:3], v[52:55], v[56:59], v[0:3]
	global_load_dwordx4 v[48:51], v[38:39], off offset:768
	global_load_dwordx4 v[52:55], v[40:41], off offset:768
	global_load_dwordx4 v[56:59], v[42:43], off offset:768
	s_waitcnt vmcnt(33)
	v_mfma_f32_16x16x32_bf16 v[4:7], v[60:63], v[68:71], v[4:7]
	v_mfma_f32_16x16x32_bf16 v[0:3], v[64:67], v[68:71], v[0:3]
	global_load_dwordx4 v[60:63], v[38:39], off offset:832
	global_load_dwordx4 v[64:67], v[40:41], off offset:832
	global_load_dwordx4 v[68:71], v[42:43], off offset:832
	s_waitcnt vmcnt(33)
	v_mfma_f32_16x16x32_bf16 v[4:7], v[72:75], v[80:83], v[4:7]
	v_mfma_f32_16x16x32_bf16 v[0:3], v[76:79], v[80:83], v[0:3]
	global_load_dwordx4 v[72:75], v[38:39], off offset:896
	global_load_dwordx4 v[76:79], v[40:41], off offset:896
	global_load_dwordx4 v[80:83], v[42:43], off offset:896
	s_waitcnt vmcnt(33)
	v_mfma_f32_16x16x32_bf16 v[4:7], v[84:87], v[92:95], v[4:7]
	v_mfma_f32_16x16x32_bf16 v[0:3], v[88:91], v[92:95], v[0:3]
	global_load_dwordx4 v[84:87], v[38:39], off offset:960
	global_load_dwordx4 v[88:91], v[40:41], off offset:960
	global_load_dwordx4 v[92:95], v[42:43], off offset:960
	s_waitcnt vmcnt(33)
	v_mfma_f32_16x16x32_bf16 v[4:7], v[96:99], v[104:107], v[4:7]
	v_mfma_f32_16x16x32_bf16 v[0:3], v[100:103], v[104:107], v[0:3]
	global_load_dwordx4 v[96:99], v[38:39], off offset:1024
	global_load_dwordx4 v[100:103], v[40:41], off offset:1024
	global_load_dwordx4 v[104:107], v[42:43], off offset:1024
	s_waitcnt vmcnt(33)
	v_mfma_f32_16x16x32_bf16 v[4:7], v[108:111], v[116:119], v[4:7]
	v_mfma_f32_16x16x32_bf16 v[0:3], v[112:115], v[116:119], v[0:3]
	global_load_dwordx4 v[108:111], v[38:39], off offset:1088
	global_load_dwordx4 v[112:115], v[40:41], off offset:1088
	global_load_dwordx4 v[116:119], v[42:43], off offset:1088
	s_waitcnt vmcnt(33)
	v_mfma_f32_16x16x32_bf16 v[4:7], v[120:123], v[128:131], v[4:7]
	v_mfma_f32_16x16x32_bf16 v[0:3], v[124:127], v[128:131], v[0:3]
	global_load_dwordx4 v[120:123], v[38:39], off offset:1152
	global_load_dwordx4 v[124:127], v[40:41], off offset:1152
	global_load_dwordx4 v[128:131], v[42:43], off offset:1152
	s_waitcnt vmcnt(33)
	v_mfma_f32_16x16x32_bf16 v[4:7], v[140:143], v[148:151], v[4:7]
	v_mfma_f32_16x16x32_bf16 v[0:3], v[144:147], v[148:151], v[0:3]
	global_load_dwordx4 v[140:143], v[38:39], off offset:1216
	global_load_dwordx4 v[144:147], v[40:41], off offset:1216
	global_load_dwordx4 v[148:151], v[42:43], off offset:1216
	s_waitcnt vmcnt(33)
; template <int MODE>
; __device__ __forceinline__ void sample_gemm(const Params& p, int l, const int tid) {
;     ...
;         for (int hh = 0; hh < 2; ++hh) {
; #pragma unroll 8
;             for (int k = hh * 1024; k < hh * 1024 + 1024; k += 32) {
;                 const bf16x8 fa0 = *(const bf16x8*)(a0 + k), fa1 = *(const bf16x8*)(a1 + k), fb = *(const bf16x8*)(bp + k);
;                 const int ci = (MODE == 2) ? hh : 0;
;                 c[ci][0] = __builtin_amdgcn_mfma_f32_16x16x32_bf16(fa0, fb, c[ci][0], 0, 0, 0);
;                 c[ci][1] = __builtin_amdgcn_mfma_f32_16x16x32_bf16(fa1, fb, c[ci][1], 0, 0, 0);
;             }
	v_mfma_f32_16x16x32_bf16 v[4:7], v[152:155], v[160:163], v[4:7]
	v_mfma_f32_16x16x32_bf16 v[0:3], v[156:159], v[160:163], v[0:3]
	global_load_dwordx4 v[152:155], v[38:39], off offset:1280
	global_load_dwordx4 v[156:159], v[40:41], off offset:1280
	global_load_dwordx4 v[160:163], v[42:43], off offset:1280
	s_waitcnt vmcnt(33)
	v_mfma_f32_16x16x32_bf16 v[4:7], v[164:167], v[172:175], v[4:7]
	v_mfma_f32_16x16x32_bf16 v[0:3], v[168:171], v[172:175], v[0:3]
	global_load_dwordx4 v[164:167], v[38:39], off offset:1344
	global_load_dwordx4 v[168:171], v[40:41], off offset:1344
	global_load_dwordx4 v[172:175], v[42:43], off offset:1344
	s_waitcnt vmcnt(33)
	v_mfma_f32_16x16x32_bf16 v[4:7], v[192:195], v[200:203], v[4:7]
	v_mfma_f32_16x16x32_bf16 v[0:3], v[196:199], v[200:203], v[0:3]
	global_load_dwordx4 v[192:195], v[38:39], off offset:1408
	global_load_dwordx4 v[196:199], v[40:41], off offset:1408
	global_load_dwordx4 v[200:203], v[42:43], off offset:1408
	s_waitcnt vmcnt(33)
	v_mfma_f32_16x16x32_bf16 v[4:7], v[216:219], v[224:227], v[4:7]
	v_mfma_f32_16x16x32_bf16 v[0:3], v[220:223], v[224:227], v[0:3]
	global_load_dwordx4 v[216:219], v[38:39], off offset:1472
	global_load_dwordx4 v[220:223], v[40:41], off offset:1472
	global_load_dwordx4 v[224:227], v[42:43], off offset:1472
	s_waitcnt vmcnt(33)
	v_mfma_f32_16x16x32_bf16 v[4:7], v[48:51], v[56:59], v[4:7]
	v_mfma_f32_16x16x32_bf16 v[0:3], v[52:55], v[56:59], v[0:3]
	global_load_dwordx4 v[48:51], v[38:39], off offset:1536
	global_load_dwordx4 v[52:55], v[40:41], off offset:1536
	global_load_dwordx4 v[56:59], v[42:43], off offset:1536
	s_waitcnt vmcnt(33)
	v_mfma_f32_16x16x32_bf16 v[4:7], v[60:63], v[68:71], v[4:7]
	v_mfma_f32_16x16x32_bf16 v[0:3], v[64:67], v[68:71], v[0:3]
	global_load_dwordx4 v[60:63], v[38:39], off offset:1600
	global_load_dwordx4 v[64:67], v[40:41], off offset:1600
	global_load_dwordx4 v[68:71], v[42:43], off offset:1600
	s_waitcnt vmcnt(33)
	v_mfma_f32_16x16x32_bf16 v[4:7], v[72:75], v[80:83], v[4:7]
	v_mfma_f32_16x16x32_bf16 v[0:3], v[76:79], v[80:83], v[0:3]
	global_load_dwordx4 v[72:75], v[38:39], off offset:1664
	global_load_dwordx4 v[76:79], v[40:41], off offset:1664
	global_load_dwordx4 v[80:83], v[42:43], off offset:1664
	s_waitcnt vmcnt(33)
	v_mfma_f32_16x16x32_bf16 v[4:7], v[84:87], v[92:95], v[4:7]
	v_mfma_f32_16x16x32_bf16 v[0:3], v[88:91], v[92:95], v[0:3]
	global_load_dwordx4 v[84:87], v[38:39], off offset:1728
	global_load_dwordx4 v[88:91], v[40:41], off offset:1728
	global_load_dwordx4 v[92:95], v[42:43], off offset:1728
	s_waitcnt vmcnt(33)
	v_mfma_f32_16x16x32_bf16 v[4:7], v[96:99], v[104:107], v[4:7]
	v_mfma_f32_16x16x32_bf16 v[0:3], v[100:103], v[104:107], v[0:3]
	global_load_dwordx4 v[96:99], v[38:39], off offset:1792
	global_load_dwordx4 v[100:103], v[40:41], off offset:1792
	global_load_dwordx4 v[104:107], v[42:43], off offset:1792
	s_waitcnt vmcnt(33)
	v_mfma_f32_16x16x32_bf16 v[4:7], v[108:111], v[116:119], v[4:7]
	v_mfma_f32_16x16x32_bf16 v[0:3], v[112:115], v[116:119], v[0:3]
	global_load_dwordx4 v[108:111], v[38:39], off offset:1856
	global_load_dwordx4 v[112:115], v[40:41], off offset:1856
	global_load_dwordx4 v[116:119], v[42:43], off offset:1856
	s_waitcnt vmcnt(33)
	v_mfma_f32_16x16x32_bf16 v[4:7], v[120:123], v[128:131], v[4:7]
	v_mfma_f32_16x16x32_bf16 v[0:3], v[124:127], v[128:131], v[0:3]
	global_load_dwordx4 v[120:123], v[38:39], off offset:1920
	global_load_dwordx4 v[124:127], v[40:41], off offset:1920
	global_load_dwordx4 v[128:131], v[42:43], off offset:1920
	s_waitcnt vmcnt(33)
	v_mfma_f32_16x16x32_bf16 v[4:7], v[140:143], v[148:151], v[4:7]
	v_mfma_f32_16x16x32_bf16 v[0:3], v[144:147], v[148:151], v[0:3]
	global_load_dwordx4 v[140:143], v[38:39], off offset:1984
	global_load_dwordx4 v[144:147], v[40:41], off offset:1984
	global_load_dwordx4 v[148:151], v[42:43], off offset:1984
	s_waitcnt vmcnt(33)
	v_mfma_f32_16x16x32_bf16 v[4:7], v[152:155], v[160:163], v[4:7]
	v_mfma_f32_16x16x32_bf16 v[0:3], v[156:159], v[160:163], v[0:3]
	global_load_dwordx4 v[152:155], v[38:39], off offset:2048
	global_load_dwordx4 v[156:159], v[40:41], off offset:2048
	global_load_dwordx4 v[160:163], v[42:43], off offset:2048
	s_waitcnt vmcnt(33)
	v_mfma_f32_16x16x32_bf16 v[4:7], v[164:167], v[172:175], v[4:7]
	v_mfma_f32_16x16x32_bf16 v[0:3], v[168:171], v[172:175], v[0:3]
	global_load_dwordx4 v[164:167], v[38:39], off offset:2112
	global_load_dwordx4 v[168:171], v[40:41], off offset:2112
	global_load_dwordx4 v[172:175], v[42:43], off offset:2112
	s_waitcnt vmcnt(33)
	v_mfma_f32_16x16x32_bf16 v[4:7], v[192:195], v[200:203], v[4:7]
	v_mfma_f32_16x16x32_bf16 v[0:3], v[196:199], v[200:203], v[0:3]
	global_load_dwordx4 v[192:195], v[38:39], off offset:2176
	global_load_dwordx4 v[196:199], v[40:41], off offset:2176
	global_load_dwordx4 v[200:203], v[42:43], off offset:2176
	s_waitcnt vmcnt(33)
	v_mfma_f32_16x16x32_bf16 v[4:7], v[216:219], v[224:227], v[4:7]
	v_mfma_f32_16x16x32_bf16 v[0:3], v[220:223], v[224:227], v[0:3]
	global_load_dwordx4 v[216:219], v[38:39], off offset:2240
	global_load_dwordx4 v[220:223], v[40:41], off offset:2240
	global_load_dwordx4 v[224:227], v[42:43], off offset:2240
	s_waitcnt vmcnt(33)
	v_mfma_f32_16x16x32_bf16 v[4:7], v[48:51], v[56:59], v[4:7]
	v_mfma_f32_16x16x32_bf16 v[0:3], v[52:55], v[56:59], v[0:3]
	global_load_dwordx4 v[48:51], v[38:39], off offset:2304
	global_load_dwordx4 v[52:55], v[40:41], off offset:2304
	global_load_dwordx4 v[56:59], v[42:43], off offset:2304
	s_waitcnt vmcnt(33)
; template <int MODE>
; __device__ __forceinline__ void sample_gemm(const Params& p, int l, const int tid) {
;     ...
;         for (int hh = 0; hh < 2; ++hh) {
; #pragma unroll 8
;             for (int k = hh * 1024; k < hh * 1024 + 1024; k += 32) {
;                 const bf16x8 fa0 = *(const bf16x8*)(a0 + k), fa1 = *(const bf16x8*)(a1 + k), fb = *(const bf16x8*)(bp + k);
;                 const int ci = (MODE == 2) ? hh : 0;
;                 c[ci][0] = __builtin_amdgcn_mfma_f32_16x16x32_bf16(fa0, fb, c[ci][0], 0, 0, 0);
;                 c[ci][1] = __builtin_amdgcn_mfma_f32_16x16x32_bf16(fa1, fb, c[ci][1], 0, 0, 0);
;             }
	v_mfma_f32_16x16x32_bf16 v[4:7], v[60:63], v[68:71], v[4:7]
	v_mfma_f32_16x16x32_bf16 v[0:3], v[64:67], v[68:71], v[0:3]
	global_load_dwordx4 v[60:63], v[38:39], off offset:2368
	global_load_dwordx4 v[64:67], v[40:41], off offset:2368
	global_load_dwordx4 v[68:71], v[42:43], off offset:2368
	s_waitcnt vmcnt(33)
	v_mfma_f32_16x16x32_bf16 v[4:7], v[72:75], v[80:83], v[4:7]
	v_mfma_f32_16x16x32_bf16 v[0:3], v[76:79], v[80:83], v[0:3]
	global_load_dwordx4 v[72:75], v[38:39], off offset:2432
	global_load_dwordx4 v[76:79], v[40:41], off offset:2432
	global_load_dwordx4 v[80:83], v[42:43], off offset:2432
	s_waitcnt vmcnt(33)
	v_mfma_f32_16x16x32_bf16 v[4:7], v[84:87], v[92:95], v[4:7]
	v_mfma_f32_16x16x32_bf16 v[0:3], v[88:91], v[92:95], v[0:3]
	global_load_dwordx4 v[84:87], v[38:39], off offset:2496
	global_load_dwordx4 v[88:91], v[40:41], off offset:2496
	global_load_dwordx4 v[92:95], v[42:43], off offset:2496
	s_waitcnt vmcnt(33)
	v_mfma_f32_16x16x32_bf16 v[4:7], v[96:99], v[104:107], v[4:7]
	v_mfma_f32_16x16x32_bf16 v[0:3], v[100:103], v[104:107], v[0:3]
	global_load_dwordx4 v[96:99], v[38:39], off offset:2560
	global_load_dwordx4 v[100:103], v[40:41], off offset:2560
	global_load_dwordx4 v[104:107], v[42:43], off offset:2560
	s_waitcnt vmcnt(33)
	v_mfma_f32_16x16x32_bf16 v[4:7], v[108:111], v[116:119], v[4:7]
	v_mfma_f32_16x16x32_bf16 v[0:3], v[112:115], v[116:119], v[0:3]
	global_load_dwordx4 v[108:111], v[38:39], off offset:2624
	global_load_dwordx4 v[112:115], v[40:41], off offset:2624
	global_load_dwordx4 v[116:119], v[42:43], off offset:2624
	s_waitcnt vmcnt(33)
	v_mfma_f32_16x16x32_bf16 v[4:7], v[120:123], v[128:131], v[4:7]
	v_mfma_f32_16x16x32_bf16 v[0:3], v[124:127], v[128:131], v[0:3]
	global_load_dwordx4 v[120:123], v[38:39], off offset:2688
	global_load_dwordx4 v[124:127], v[40:41], off offset:2688
	global_load_dwordx4 v[128:131], v[42:43], off offset:2688
	s_waitcnt vmcnt(33)
	v_mfma_f32_16x16x32_bf16 v[4:7], v[140:143], v[148:151], v[4:7]
	v_mfma_f32_16x16x32_bf16 v[0:3], v[144:147], v[148:151], v[0:3]
	global_load_dwordx4 v[140:143], v[38:39], off offset:2752
	global_load_dwordx4 v[144:147], v[40:41], off offset:2752
	global_load_dwordx4 v[148:151], v[42:43], off offset:2752
	s_waitcnt vmcnt(33)
	v_mfma_f32_16x16x32_bf16 v[12:15], v[152:155], v[160:163], v[12:15]
	v_mfma_f32_16x16x32_bf16 v[8:11], v[156:159], v[160:163], v[8:11]
	global_load_dwordx4 v[152:155], v[38:39], off offset:2816
	global_load_dwordx4 v[156:159], v[40:41], off offset:2816
	global_load_dwordx4 v[160:163], v[42:43], off offset:2816
	s_waitcnt vmcnt(33)
	v_mfma_f32_16x16x32_bf16 v[12:15], v[164:167], v[172:175], v[12:15]
	v_mfma_f32_16x16x32_bf16 v[8:11], v[168:171], v[172:175], v[8:11]
	global_load_dwordx4 v[164:167], v[38:39], off offset:2880
	global_load_dwordx4 v[168:171], v[40:41], off offset:2880
	global_load_dwordx4 v[172:175], v[42:43], off offset:2880
	s_waitcnt vmcnt(33)
	v_mfma_f32_16x16x32_bf16 v[12:15], v[192:195], v[200:203], v[12:15]
	v_mfma_f32_16x16x32_bf16 v[8:11], v[196:199], v[200:203], v[8:11]
	global_load_dwordx4 v[192:195], v[38:39], off offset:2944
	global_load_dwordx4 v[196:199], v[40:41], off offset:2944
	global_load_dwordx4 v[200:203], v[42:43], off offset:2944
	s_waitcnt vmcnt(33)
	v_mfma_f32_16x16x32_bf16 v[12:15], v[216:219], v[224:227], v[12:15]
	v_mfma_f32_16x16x32_bf16 v[8:11], v[220:223], v[224:227], v[8:11]
	global_load_dwordx4 v[216:219], v[38:39], off offset:3008
	global_load_dwordx4 v[220:223], v[40:41], off offset:3008
	global_load_dwordx4 v[224:227], v[42:43], off offset:3008
	s_waitcnt vmcnt(33)
	v_mfma_f32_16x16x32_bf16 v[12:15], v[48:51], v[56:59], v[12:15]
	v_mfma_f32_16x16x32_bf16 v[8:11], v[52:55], v[56:59], v[8:11]
	global_load_dwordx4 v[48:51], v[38:39], off offset:3072
	global_load_dwordx4 v[52:55], v[40:41], off offset:3072
	global_load_dwordx4 v[56:59], v[42:43], off offset:3072
	s_waitcnt vmcnt(33)
	v_mfma_f32_16x16x32_bf16 v[12:15], v[60:63], v[68:71], v[12:15]
	v_mfma_f32_16x16x32_bf16 v[8:11], v[64:67], v[68:71], v[8:11]
	global_load_dwordx4 v[60:63], v[38:39], off offset:3136
	global_load_dwordx4 v[64:67], v[40:41], off offset:3136
	global_load_dwordx4 v[68:71], v[42:43], off offset:3136
	s_waitcnt vmcnt(33)
	v_mfma_f32_16x16x32_bf16 v[12:15], v[72:75], v[80:83], v[12:15]
	v_mfma_f32_16x16x32_bf16 v[8:11], v[76:79], v[80:83], v[8:11]
	global_load_dwordx4 v[72:75], v[38:39], off offset:3200
	global_load_dwordx4 v[76:79], v[40:41], off offset:3200
	global_load_dwordx4 v[80:83], v[42:43], off offset:3200
	s_waitcnt vmcnt(33)
	v_mfma_f32_16x16x32_bf16 v[12:15], v[84:87], v[92:95], v[12:15]
	v_mfma_f32_16x16x32_bf16 v[8:11], v[88:91], v[92:95], v[8:11]
	global_load_dwordx4 v[84:87], v[38:39], off offset:3264
	global_load_dwordx4 v[88:91], v[40:41], off offset:3264
	global_load_dwordx4 v[92:95], v[42:43], off offset:3264
	s_waitcnt vmcnt(33)
	v_mfma_f32_16x16x32_bf16 v[12:15], v[96:99], v[104:107], v[12:15]
	v_mfma_f32_16x16x32_bf16 v[8:11], v[100:103], v[104:107], v[8:11]
	global_load_dwordx4 v[96:99], v[38:39], off offset:3328
	global_load_dwordx4 v[100:103], v[40:41], off offset:3328
	global_load_dwordx4 v[104:107], v[42:43], off offset:3328
	s_waitcnt vmcnt(33)
	v_mfma_f32_16x16x32_bf16 v[12:15], v[108:111], v[116:119], v[12:15]
	v_mfma_f32_16x16x32_bf16 v[8:11], v[112:115], v[116:119], v[8:11]
	global_load_dwordx4 v[108:111], v[38:39], off offset:3392
	global_load_dwordx4 v[112:115], v[40:41], off offset:3392
	global_load_dwordx4 v[116:119], v[42:43], off offset:3392
	s_waitcnt vmcnt(33)
; template <int MODE>
; __device__ __forceinline__ void sample_gemm(const Params& p, int l, const int tid) {
;     ...
;         for (int hh = 0; hh < 2; ++hh) {
; #pragma unroll 8
;             for (int k = hh * 1024; k < hh * 1024 + 1024; k += 32) {
;                 const bf16x8 fa0 = *(const bf16x8*)(a0 + k), fa1 = *(const bf16x8*)(a1 + k), fb = *(const bf16x8*)(bp + k);
;                 const int ci = (MODE == 2) ? hh : 0;
;                 c[ci][0] = __builtin_amdgcn_mfma_f32_16x16x32_bf16(fa0, fb, c[ci][0], 0, 0, 0);
;                 c[ci][1] = __builtin_amdgcn_mfma_f32_16x16x32_bf16(fa1, fb, c[ci][1], 0, 0, 0);
;             }
	v_mfma_f32_16x16x32_bf16 v[12:15], v[120:123], v[128:131], v[12:15]
	v_mfma_f32_16x16x32_bf16 v[8:11], v[124:127], v[128:131], v[8:11]
	global_load_dwordx4 v[120:123], v[38:39], off offset:3456
	global_load_dwordx4 v[124:127], v[40:41], off offset:3456
	global_load_dwordx4 v[128:131], v[42:43], off offset:3456
	s_waitcnt vmcnt(33)
	v_mfma_f32_16x16x32_bf16 v[12:15], v[140:143], v[148:151], v[12:15]
	v_mfma_f32_16x16x32_bf16 v[8:11], v[144:147], v[148:151], v[8:11]
	global_load_dwordx4 v[140:143], v[38:39], off offset:3520
	global_load_dwordx4 v[144:147], v[40:41], off offset:3520
	global_load_dwordx4 v[148:151], v[42:43], off offset:3520
	s_waitcnt vmcnt(33)
	v_mfma_f32_16x16x32_bf16 v[12:15], v[152:155], v[160:163], v[12:15]
	v_mfma_f32_16x16x32_bf16 v[8:11], v[156:159], v[160:163], v[8:11]
	global_load_dwordx4 v[152:155], v[38:39], off offset:3584
	global_load_dwordx4 v[156:159], v[40:41], off offset:3584
	global_load_dwordx4 v[160:163], v[42:43], off offset:3584
	s_waitcnt vmcnt(33)
	v_mfma_f32_16x16x32_bf16 v[12:15], v[164:167], v[172:175], v[12:15]
	v_mfma_f32_16x16x32_bf16 v[8:11], v[168:171], v[172:175], v[8:11]
	global_load_dwordx4 v[164:167], v[38:39], off offset:3648
	global_load_dwordx4 v[168:171], v[40:41], off offset:3648
	global_load_dwordx4 v[172:175], v[42:43], off offset:3648
	s_waitcnt vmcnt(33)
	v_mfma_f32_16x16x32_bf16 v[12:15], v[192:195], v[200:203], v[12:15]
	v_mfma_f32_16x16x32_bf16 v[8:11], v[196:199], v[200:203], v[8:11]
	global_load_dwordx4 v[192:195], v[38:39], off offset:3712
	global_load_dwordx4 v[196:199], v[40:41], off offset:3712
	global_load_dwordx4 v[200:203], v[42:43], off offset:3712
	s_waitcnt vmcnt(33)
	v_mfma_f32_16x16x32_bf16 v[12:15], v[216:219], v[224:227], v[12:15]
	v_mfma_f32_16x16x32_bf16 v[8:11], v[220:223], v[224:227], v[8:11]
	global_load_dwordx4 v[216:219], v[38:39], off offset:3776
	global_load_dwordx4 v[220:223], v[40:41], off offset:3776
	global_load_dwordx4 v[224:227], v[42:43], off offset:3776
	s_waitcnt vmcnt(33)
	v_mfma_f32_16x16x32_bf16 v[12:15], v[48:51], v[56:59], v[12:15]
	v_mfma_f32_16x16x32_bf16 v[8:11], v[52:55], v[56:59], v[8:11]
	global_load_dwordx4 v[48:51], v[38:39], off offset:3840
	global_load_dwordx4 v[52:55], v[40:41], off offset:3840
	global_load_dwordx4 v[56:59], v[42:43], off offset:3840
	s_waitcnt vmcnt(33)
	v_mfma_f32_16x16x32_bf16 v[12:15], v[60:63], v[68:71], v[12:15]
	v_mfma_f32_16x16x32_bf16 v[8:11], v[64:67], v[68:71], v[8:11]
	global_load_dwordx4 v[60:63], v[38:39], off offset:3904
	global_load_dwordx4 v[64:67], v[40:41], off offset:3904
	global_load_dwordx4 v[68:71], v[42:43], off offset:3904
	s_waitcnt vmcnt(33)
	v_mfma_f32_16x16x32_bf16 v[12:15], v[72:75], v[80:83], v[12:15]
	v_mfma_f32_16x16x32_bf16 v[8:11], v[76:79], v[80:83], v[8:11]
	global_load_dwordx4 v[72:75], v[38:39], off offset:3968
	global_load_dwordx4 v[76:79], v[40:41], off offset:3968
	global_load_dwordx4 v[80:83], v[42:43], off offset:3968
	s_waitcnt vmcnt(33)
	v_mfma_f32_16x16x32_bf16 v[12:15], v[84:87], v[92:95], v[12:15]
	v_mfma_f32_16x16x32_bf16 v[8:11], v[88:91], v[92:95], v[8:11]
	global_load_dwordx4 v[84:87], v[38:39], off offset:4032
	global_load_dwordx4 v[88:91], v[40:41], off offset:4032
	global_load_dwordx4 v[92:95], v[42:43], off offset:4032
	s_waitcnt vmcnt(33)
	v_mfma_f32_16x16x32_bf16 v[12:15], v[96:99], v[104:107], v[12:15]
	v_mfma_f32_16x16x32_bf16 v[8:11], v[100:103], v[104:107], v[8:11]
	s_waitcnt vmcnt(30)
	v_mfma_f32_16x16x32_bf16 v[12:15], v[108:111], v[116:119], v[12:15]
	v_mfma_f32_16x16x32_bf16 v[8:11], v[112:115], v[116:119], v[8:11]
	s_waitcnt vmcnt(27)
	v_mfma_f32_16x16x32_bf16 v[12:15], v[120:123], v[128:131], v[12:15]
	v_mfma_f32_16x16x32_bf16 v[8:11], v[124:127], v[128:131], v[8:11]
	s_waitcnt vmcnt(24)
	v_mfma_f32_16x16x32_bf16 v[12:15], v[140:143], v[148:151], v[12:15]
	v_mfma_f32_16x16x32_bf16 v[8:11], v[144:147], v[148:151], v[8:11]
	s_waitcnt vmcnt(21)
	v_mfma_f32_16x16x32_bf16 v[12:15], v[152:155], v[160:163], v[12:15]
	v_mfma_f32_16x16x32_bf16 v[8:11], v[156:159], v[160:163], v[8:11]
	s_waitcnt vmcnt(18)
	v_mfma_f32_16x16x32_bf16 v[12:15], v[164:167], v[172:175], v[12:15]
	v_mfma_f32_16x16x32_bf16 v[8:11], v[168:171], v[172:175], v[8:11]
	s_waitcnt vmcnt(15)
	v_mfma_f32_16x16x32_bf16 v[12:15], v[192:195], v[200:203], v[12:15]
	v_mfma_f32_16x16x32_bf16 v[8:11], v[196:199], v[200:203], v[8:11]
	s_waitcnt vmcnt(12)
	v_mfma_f32_16x16x32_bf16 v[12:15], v[216:219], v[224:227], v[12:15]
	v_mfma_f32_16x16x32_bf16 v[8:11], v[220:223], v[224:227], v[8:11]
	s_waitcnt vmcnt(9)
	v_mfma_f32_16x16x32_bf16 v[12:15], v[48:51], v[56:59], v[12:15]
	v_mfma_f32_16x16x32_bf16 v[8:11], v[52:55], v[56:59], v[8:11]
	s_waitcnt vmcnt(6)
; __device__ __forceinline__ float bf2f(bf16_t v) { return __uint_as_float(((unsigned)v) << 16); }
; __device__ __forceinline__ bf16_t f2bf(float f) { return (bf16_t)(pk2(f, 0.f) & 0xffffu); }
; template <int MODE>
; __device__ __forceinline__ void sample_gemm(const Params& p, int l, const int tid) {
;     ...
;             for (int k = hh * 1024; k < hh * 1024 + 1024; k += 32) {
;                 const bf16x8 fa0 = *(const bf16x8*)(a0 + k), fa1 = *(const bf16x8*)(a1 + k), fb = *(const bf16x8*)(bp + k);
;                 const int ci = (MODE == 2) ? hh : 0;
;                 c[ci][0] = __builtin_amdgcn_mfma_f32_16x16x32_bf16(fa0, fb, c[ci][0], 0, 0, 0);
;                 c[ci][1] = __builtin_amdgcn_mfma_f32_16x16x32_bf16(fa1, fb, c[ci][1], 0, 0, 0);
;             }
;     ...
;         const int col = n0 + r16;
; #pragma unroll
;         for (int i = 0; i < 2; ++i)
; #pragma unroll
;             for (int j = 0; j < 4; ++j) {
;                 const int row = MP + wid * 32 + i * 16 + quad * 4 + j;
;                 if (MODE == 2) {
;                     const float sa = bf2f(((const bf16_t*)(p.ws + WS_MA))[(size_t)row * 2048 + col]), sb = bf2f(((const bf16_t*)(p.ws + WS_MB))[(size_t)row * 2048 + col]);
;                     ((bf16_t*)(p.ws + WS_MERGED))[(size_t)row * 2048 + col] = f2bf(sa * c[0][i][j] + sb * c[1][i][j]);
	v_mfma_f32_16x16x32_bf16 v[12:15], v[60:63], v[68:71], v[12:15]
	v_mfma_f32_16x16x32_bf16 v[8:11], v[64:67], v[68:71], v[8:11]
	s_waitcnt vmcnt(3)
	v_mfma_f32_16x16x32_bf16 v[12:15], v[72:75], v[80:83], v[12:15]
	v_mfma_f32_16x16x32_bf16 v[8:11], v[76:79], v[80:83], v[8:11]
	s_waitcnt vmcnt(0)
	v_mfma_f32_16x16x32_bf16 v[12:15], v[84:87], v[92:95], v[12:15]
	v_mfma_f32_16x16x32_bf16 v[8:11], v[88:91], v[92:95], v[8:11]
	v_lshl_or_b32 v36, s10, 4, v44
	v_ashrrev_i32_e32 v37, 31, v36
	v_lshl_add_u64 v[38:39], v[18:19], 0, v[36:37]
	v_lshlrev_b64 v[48:49], 1, v[38:39]
	v_lshl_add_u64 v[40:41], s[4:5], 0, v[48:49]
	global_load_ushort v64, v[40:41], off
	v_lshl_add_u64 v[40:41], s[6:7], 0, v[48:49]
	global_load_ushort v72, v[40:41], off
	v_lshl_add_u64 v[38:39], v[20:21], 0, v[36:37]
	v_lshlrev_b64 v[50:51], 1, v[38:39]
	v_lshl_add_u64 v[40:41], s[4:5], 0, v[50:51]
	global_load_ushort v65, v[40:41], off
	v_lshl_add_u64 v[40:41], s[6:7], 0, v[50:51]
	global_load_ushort v73, v[40:41], off
	v_lshl_add_u64 v[38:39], v[22:23], 0, v[36:37]
	v_lshlrev_b64 v[52:53], 1, v[38:39]
	v_lshl_add_u64 v[40:41], s[4:5], 0, v[52:53]
	global_load_ushort v66, v[40:41], off
	v_lshl_add_u64 v[40:41], s[6:7], 0, v[52:53]
	global_load_ushort v74, v[40:41], off
	v_lshl_add_u64 v[38:39], v[24:25], 0, v[36:37]
	v_lshlrev_b64 v[54:55], 1, v[38:39]
	v_lshl_add_u64 v[40:41], s[4:5], 0, v[54:55]
	global_load_ushort v67, v[40:41], off
	v_lshl_add_u64 v[40:41], s[6:7], 0, v[54:55]
	global_load_ushort v75, v[40:41], off
	v_lshl_add_u64 v[38:39], v[16:17], 0, v[36:37]
	v_lshlrev_b64 v[56:57], 1, v[38:39]
	v_lshl_add_u64 v[40:41], s[4:5], 0, v[56:57]
	global_load_ushort v68, v[40:41], off
	v_lshl_add_u64 v[40:41], s[6:7], 0, v[56:57]
	global_load_ushort v76, v[40:41], off
	v_lshl_add_u64 v[38:39], v[26:27], 0, v[36:37]
	v_lshlrev_b64 v[58:59], 1, v[38:39]
	v_lshl_add_u64 v[40:41], s[4:5], 0, v[58:59]
	global_load_ushort v69, v[40:41], off
	v_lshl_add_u64 v[40:41], s[6:7], 0, v[58:59]
	global_load_ushort v77, v[40:41], off
	v_lshl_add_u64 v[38:39], v[28:29], 0, v[36:37]
	v_lshlrev_b64 v[60:61], 1, v[38:39]
	v_lshl_add_u64 v[40:41], s[4:5], 0, v[60:61]
	global_load_ushort v70, v[40:41], off
	v_lshl_add_u64 v[40:41], s[6:7], 0, v[60:61]
	global_load_ushort v78, v[40:41], off
	v_lshl_add_u64 v[38:39], v[30:31], 0, v[36:37]
	v_lshlrev_b64 v[62:63], 1, v[38:39]
	v_lshl_add_u64 v[40:41], s[4:5], 0, v[62:63]
	global_load_ushort v71, v[40:41], off
	v_lshl_add_u64 v[40:41], s[6:7], 0, v[62:63]
	global_load_ushort v79, v[40:41], off
	v_readlane_b32 s12, v248, 0
	v_readlane_b32 s11, v247, 30
	v_readlane_b32 s13, v248, 1
	s_nop 1
	s_add_i32 s10, s10, s12
	v_add_u32_e32 v34, s11, v34
	s_waitcnt vmcnt(0)
	v_lshlrev_b32_e32 v64, 16, v64
	v_lshlrev_b32_e32 v72, 16, v72
	v_mul_f32_e32 v80, v12, v72
	v_fmac_f32_e32 v80, v4, v64
	v_cvt_pk_bf16_f32 v80, v80, v80
	v_lshl_add_u64 v[40:41], s[8:9], 0, v[48:49]
	global_store_short v[40:41], v80, off
	v_lshlrev_b32_e32 v65, 16, v65
	v_lshlrev_b32_e32 v73, 16, v73
	v_mul_f32_e32 v81, v13, v73
	v_fmac_f32_e32 v81, v5, v65
	v_cvt_pk_bf16_f32 v81, v81, v81
	v_lshl_add_u64 v[40:41], s[8:9], 0, v[50:51]
	global_store_short v[40:41], v81, off
	v_lshlrev_b32_e32 v66, 16, v66
	v_lshlrev_b32_e32 v74, 16, v74
	v_mul_f32_e32 v82, v14, v74
	v_fmac_f32_e32 v82, v6, v66
	v_cvt_pk_bf16_f32 v82, v82, v82
	v_lshl_add_u64 v[40:41], s[8:9], 0, v[52:53]
	global_store_short v[40:41], v82, off
	v_lshlrev_b32_e32 v67, 16, v67
	v_lshlrev_b32_e32 v75, 16, v75
	v_mul_f32_e32 v83, v15, v75
	v_fmac_f32_e32 v83, v7, v67
	v_cvt_pk_bf16_f32 v83, v83, v83
	v_lshl_add_u64 v[40:41], s[8:9], 0, v[54:55]
	global_store_short v[40:41], v83, off
	v_lshlrev_b32_e32 v68, 16, v68
	v_lshlrev_b32_e32 v76, 16, v76
	v_mul_f32_e32 v84, v8, v76
	v_fmac_f32_e32 v84, v0, v68
	v_cvt_pk_bf16_f32 v84, v84, v84
	v_lshl_add_u64 v[40:41], s[8:9], 0, v[56:57]
	global_store_short v[40:41], v84, off
	v_lshlrev_b32_e32 v69, 16, v69
	v_lshlrev_b32_e32 v77, 16, v77
	v_mul_f32_e32 v85, v9, v77
	v_fmac_f32_e32 v85, v1, v69
	v_cvt_pk_bf16_f32 v85, v85, v85
	v_lshl_add_u64 v[40:41], s[8:9], 0, v[58:59]
	global_store_short v[40:41], v85, off
	v_lshlrev_b32_e32 v70, 16, v70
	v_lshlrev_b32_e32 v78, 16, v78
	v_mul_f32_e32 v86, v10, v78
	v_fmac_f32_e32 v86, v2, v70
	v_cvt_pk_bf16_f32 v86, v86, v86
	v_lshl_add_u64 v[40:41], s[8:9], 0, v[60:61]
	global_store_short v[40:41], v86, off
	v_lshlrev_b32_e32 v71, 16, v71
	v_lshlrev_b32_e32 v79, 16, v79
	v_mul_f32_e32 v87, v11, v79
	v_fmac_f32_e32 v87, v3, v71
	v_cvt_pk_bf16_f32 v87, v87, v87
	v_lshl_add_u64 v[40:41], s[8:9], 0, v[62:63]
	global_store_short v[40:41], v87, off
	s_cmpk_gt_i32 s10, 0x7f
	s_cbranch_scc0 .LBB0_17

; template <int MODE>
; __device__ __forceinline__ void sample_gemm(const Params& p, int l, const int tid) {
;     ...
;         const bf16_t* a0 = A + (size_t)(wid * 32 + r16) * 2048 + quad * 8; const bf16_t* a1 = a0 + 16 * 2048; const bf16_t* bp = Bt + (size_t)(n0 + r16) * 2048 + quad * 8;
;         f32x4 c[2][2];
; #pragma unroll
;         for (int i = 0; i < 2; ++i)
; #pragma unroll
;             for (int j = 0; j < 2; ++j) c[i][j] = (f32x4){0.f, 0.f, 0.f, 0.f};
; #pragma unroll
;         for (int hh = 0; hh < 2; ++hh) {
; #pragma unroll 8
;             for (int k = hh * 1024; k < hh * 1024 + 1024; k += 32) {
;                 const bf16x8 fa0 = *(const bf16x8*)(a0 + k), fa1 = *(const bf16x8*)(a1 + k), fb = *(const bf16x8*)(bp + k);
;                 const int ci = (MODE == 2) ? hh : 0;
;                 c[ci][0] = __builtin_amdgcn_mfma_f32_16x16x32_bf16(fa0, fb, c[ci][0], 0, 0, 0);
;                 c[ci][1] = __builtin_amdgcn_mfma_f32_16x16x32_bf16(fa1, fb, c[ci][1], 0, 0, 0);
;             }
.LBB0_709:
	v_ashrrev_i32_e32 v59, 31, v58
	v_lshlrev_b64 v[0:1], 12, v[58:59]
	v_lshl_add_u64 v[60:61], s[8:9], 0, v[0:1]
	v_mov_b32_e32 v4, 0
	s_movk_i32 s5, 0xffe0
	v_mov_b64_e32 v[62:63], v[60:61]
	v_mov_b64_e32 v[64:65], v[56:57]
	v_mov_b32_e32 v5, v4
	v_mov_b32_e32 v6, v4
	v_mov_b32_e32 v7, v4
	v_mov_b32_e32 v0, v4
	v_mov_b32_e32 v1, v4
	v_mov_b32_e32 v2, v4
	v_mov_b32_e32 v3, v4
	v_lshl_add_u64 v[62:63], v[56:57], 0, v[136:137]
	v_lshl_add_u64 v[66:67], v[60:61], 0, v[136:137]
	s_mov_b64 s[12:13], 0x14200000
	v_lshl_add_u64 v[62:63], v[62:63], 0, s[12:13]
	s_mov_b64 s[12:13], 0x10000
	v_lshl_add_u64 v[64:65], v[62:63], 0, s[12:13]
	s_mov_b64 s[12:13], 0x3900000
	v_lshl_add_u64 v[66:67], v[66:67], 0, s[12:13]
	global_load_dwordx4 v[72:75], v[62:63], off
	global_load_dwordx4 v[76:79], v[64:65], off
	global_load_dwordx4 v[80:83], v[66:67], off
	global_load_dwordx4 v[84:87], v[62:63], off offset:64
	global_load_dwordx4 v[88:91], v[64:65], off offset:64
	global_load_dwordx4 v[92:95], v[66:67], off offset:64
	global_load_dwordx4 v[96:99], v[62:63], off offset:128
	global_load_dwordx4 v[100:103], v[64:65], off offset:128
	global_load_dwordx4 v[104:107], v[66:67], off offset:128
	global_load_dwordx4 v[108:111], v[62:63], off offset:192
	global_load_dwordx4 v[112:115], v[64:65], off offset:192
	global_load_dwordx4 v[116:119], v[66:67], off offset:192
	global_load_dwordx4 v[120:123], v[62:63], off offset:256
	global_load_dwordx4 v[124:127], v[64:65], off offset:256
	global_load_dwordx4 v[128:131], v[66:67], off offset:256
	global_load_dwordx4 v[140:143], v[62:63], off offset:320
	global_load_dwordx4 v[144:147], v[64:65], off offset:320
	global_load_dwordx4 v[148:151], v[66:67], off offset:320
	global_load_dwordx4 v[152:155], v[62:63], off offset:384
	global_load_dwordx4 v[156:159], v[64:65], off offset:384
	global_load_dwordx4 v[160:163], v[66:67], off offset:384
	global_load_dwordx4 v[164:167], v[62:63], off offset:448
	global_load_dwordx4 v[168:171], v[64:65], off offset:448
	global_load_dwordx4 v[172:175], v[66:67], off offset:448
	global_load_dwordx4 v[192:195], v[62:63], off offset:512
	global_load_dwordx4 v[196:199], v[64:65], off offset:512
	global_load_dwordx4 v[200:203], v[66:67], off offset:512
	global_load_dwordx4 v[216:219], v[62:63], off offset:576
	global_load_dwordx4 v[220:223], v[64:65], off offset:576
	global_load_dwordx4 v[224:227], v[66:67], off offset:576
	global_load_dwordx4 v[228:231], v[62:63], off offset:640
	global_load_dwordx4 v[232:235], v[64:65], off offset:640
	global_load_dwordx4 v[236:239], v[66:67], off offset:640
	s_waitcnt vmcnt(30)
	v_mfma_f32_16x16x32_bf16 v[4:7], v[72:75], v[80:83], v[4:7]
	v_mfma_f32_16x16x32_bf16 v[0:3], v[76:79], v[80:83], v[0:3]
	global_load_dwordx4 v[72:75], v[62:63], off offset:704
	global_load_dwordx4 v[76:79], v[64:65], off offset:704
	global_load_dwordx4 v[80:83], v[66:67], off offset:704
	s_waitcnt vmcnt(30)
	v_mfma_f32_16x16x32_bf16 v[4:7], v[84:87], v[92:95], v[4:7]
	v_mfma_f32_16x16x32_bf16 v[0:3], v[88:91], v[92:95], v[0:3]
	global_load_dwordx4 v[84:87], v[62:63], off offset:768
	global_load_dwordx4 v[88:91], v[64:65], off offset:768
	global_load_dwordx4 v[92:95], v[66:67], off offset:768
	s_waitcnt vmcnt(30)
	v_mfma_f32_16x16x32_bf16 v[4:7], v[96:99], v[104:107], v[4:7]
	v_mfma_f32_16x16x32_bf16 v[0:3], v[100:103], v[104:107], v[0:3]
	global_load_dwordx4 v[96:99], v[62:63], off offset:832
	global_load_dwordx4 v[100:103], v[64:65], off offset:832
	global_load_dwordx4 v[104:107], v[66:67], off offset:832
	s_waitcnt vmcnt(30)
	v_mfma_f32_16x16x32_bf16 v[4:7], v[108:111], v[116:119], v[4:7]
	v_mfma_f32_16x16x32_bf16 v[0:3], v[112:115], v[116:119], v[0:3]
	global_load_dwordx4 v[108:111], v[62:63], off offset:896
	global_load_dwordx4 v[112:115], v[64:65], off offset:896
	global_load_dwordx4 v[116:119], v[66:67], off offset:896
	s_waitcnt vmcnt(30)
	v_mfma_f32_16x16x32_bf16 v[4:7], v[120:123], v[128:131], v[4:7]
	v_mfma_f32_16x16x32_bf16 v[0:3], v[124:127], v[128:131], v[0:3]
	global_load_dwordx4 v[120:123], v[62:63], off offset:960
	global_load_dwordx4 v[124:127], v[64:65], off offset:960
	global_load_dwordx4 v[128:131], v[66:67], off offset:960
	s_waitcnt vmcnt(30)
	v_mfma_f32_16x16x32_bf16 v[4:7], v[140:143], v[148:151], v[4:7]
	v_mfma_f32_16x16x32_bf16 v[0:3], v[144:147], v[148:151], v[0:3]
	global_load_dwordx4 v[140:143], v[62:63], off offset:1024
	global_load_dwordx4 v[144:147], v[64:65], off offset:1024
	global_load_dwordx4 v[148:151], v[66:67], off offset:1024
	s_waitcnt vmcnt(30)
	v_mfma_f32_16x16x32_bf16 v[4:7], v[152:155], v[160:163], v[4:7]
	v_mfma_f32_16x16x32_bf16 v[0:3], v[156:159], v[160:163], v[0:3]
	global_load_dwordx4 v[152:155], v[62:63], off offset:1088
	global_load_dwordx4 v[156:159], v[64:65], off offset:1088
	global_load_dwordx4 v[160:163], v[66:67], off offset:1088
	s_waitcnt vmcnt(30)
	v_mfma_f32_16x16x32_bf16 v[4:7], v[164:167], v[172:175], v[4:7]
	v_mfma_f32_16x16x32_bf16 v[0:3], v[168:171], v[172:175], v[0:3]
	global_load_dwordx4 v[164:167], v[62:63], off offset:1152
	global_load_dwordx4 v[168:171], v[64:65], off offset:1152
	global_load_dwordx4 v[172:175], v[66:67], off offset:1152
	s_waitcnt vmcnt(30)
	v_mfma_f32_16x16x32_bf16 v[4:7], v[192:195], v[200:203], v[4:7]
	v_mfma_f32_16x16x32_bf16 v[0:3], v[196:199], v[200:203], v[0:3]
	global_load_dwordx4 v[192:195], v[62:63], off offset:1216
	global_load_dwordx4 v[196:199], v[64:65], off offset:1216
	global_load_dwordx4 v[200:203], v[66:67], off offset:1216
	s_waitcnt vmcnt(30)
; template <int MODE>
; __device__ __forceinline__ void sample_gemm(const Params& p, int l, const int tid) {
;     ...
;         for (int hh = 0; hh < 2; ++hh) {
; #pragma unroll 8
;             for (int k = hh * 1024; k < hh * 1024 + 1024; k += 32) {
;                 const bf16x8 fa0 = *(const bf16x8*)(a0 + k), fa1 = *(const bf16x8*)(a1 + k), fb = *(const bf16x8*)(bp + k);
;                 const int ci = (MODE == 2) ? hh : 0;
;                 c[ci][0] = __builtin_amdgcn_mfma_f32_16x16x32_bf16(fa0, fb, c[ci][0], 0, 0, 0);
;                 c[ci][1] = __builtin_amdgcn_mfma_f32_16x16x32_bf16(fa1, fb, c[ci][1], 0, 0, 0);
;             }
	v_mfma_f32_16x16x32_bf16 v[4:7], v[216:219], v[224:227], v[4:7]
	v_mfma_f32_16x16x32_bf16 v[0:3], v[220:223], v[224:227], v[0:3]
	global_load_dwordx4 v[216:219], v[62:63], off offset:1280
	global_load_dwordx4 v[220:223], v[64:65], off offset:1280
	global_load_dwordx4 v[224:227], v[66:67], off offset:1280
	s_waitcnt vmcnt(30)
	v_mfma_f32_16x16x32_bf16 v[4:7], v[228:231], v[236:239], v[4:7]
	v_mfma_f32_16x16x32_bf16 v[0:3], v[232:235], v[236:239], v[0:3]
	global_load_dwordx4 v[228:231], v[62:63], off offset:1344
	global_load_dwordx4 v[232:235], v[64:65], off offset:1344
	global_load_dwordx4 v[236:239], v[66:67], off offset:1344
	s_waitcnt vmcnt(30)
	v_mfma_f32_16x16x32_bf16 v[4:7], v[72:75], v[80:83], v[4:7]
	v_mfma_f32_16x16x32_bf16 v[0:3], v[76:79], v[80:83], v[0:3]
	global_load_dwordx4 v[72:75], v[62:63], off offset:1408
	global_load_dwordx4 v[76:79], v[64:65], off offset:1408
	global_load_dwordx4 v[80:83], v[66:67], off offset:1408
	s_waitcnt vmcnt(30)
	v_mfma_f32_16x16x32_bf16 v[4:7], v[84:87], v[92:95], v[4:7]
	v_mfma_f32_16x16x32_bf16 v[0:3], v[88:91], v[92:95], v[0:3]
	global_load_dwordx4 v[84:87], v[62:63], off offset:1472
	global_load_dwordx4 v[88:91], v[64:65], off offset:1472
	global_load_dwordx4 v[92:95], v[66:67], off offset:1472
	s_waitcnt vmcnt(30)
	v_mfma_f32_16x16x32_bf16 v[4:7], v[96:99], v[104:107], v[4:7]
	v_mfma_f32_16x16x32_bf16 v[0:3], v[100:103], v[104:107], v[0:3]
	global_load_dwordx4 v[96:99], v[62:63], off offset:1536
	global_load_dwordx4 v[100:103], v[64:65], off offset:1536
	global_load_dwordx4 v[104:107], v[66:67], off offset:1536
	s_waitcnt vmcnt(30)
	v_mfma_f32_16x16x32_bf16 v[4:7], v[108:111], v[116:119], v[4:7]
	v_mfma_f32_16x16x32_bf16 v[0:3], v[112:115], v[116:119], v[0:3]
	global_load_dwordx4 v[108:111], v[62:63], off offset:1600
	global_load_dwordx4 v[112:115], v[64:65], off offset:1600
	global_load_dwordx4 v[116:119], v[66:67], off offset:1600
	s_waitcnt vmcnt(30)
	v_mfma_f32_16x16x32_bf16 v[4:7], v[120:123], v[128:131], v[4:7]
	v_mfma_f32_16x16x32_bf16 v[0:3], v[124:127], v[128:131], v[0:3]
	global_load_dwordx4 v[120:123], v[62:63], off offset:1664
	global_load_dwordx4 v[124:127], v[64:65], off offset:1664
	global_load_dwordx4 v[128:131], v[66:67], off offset:1664
	s_waitcnt vmcnt(30)
	v_mfma_f32_16x16x32_bf16 v[4:7], v[140:143], v[148:151], v[4:7]
	v_mfma_f32_16x16x32_bf16 v[0:3], v[144:147], v[148:151], v[0:3]
	global_load_dwordx4 v[140:143], v[62:63], off offset:1728
	global_load_dwordx4 v[144:147], v[64:65], off offset:1728
	global_load_dwordx4 v[148:151], v[66:67], off offset:1728
	s_waitcnt vmcnt(30)
	v_mfma_f32_16x16x32_bf16 v[4:7], v[152:155], v[160:163], v[4:7]
	v_mfma_f32_16x16x32_bf16 v[0:3], v[156:159], v[160:163], v[0:3]
	global_load_dwordx4 v[152:155], v[62:63], off offset:1792
	global_load_dwordx4 v[156:159], v[64:65], off offset:1792
	global_load_dwordx4 v[160:163], v[66:67], off offset:1792
	s_waitcnt vmcnt(30)
	v_mfma_f32_16x16x32_bf16 v[4:7], v[164:167], v[172:175], v[4:7]
	v_mfma_f32_16x16x32_bf16 v[0:3], v[168:171], v[172:175], v[0:3]
	global_load_dwordx4 v[164:167], v[62:63], off offset:1856
	global_load_dwordx4 v[168:171], v[64:65], off offset:1856
	global_load_dwordx4 v[172:175], v[66:67], off offset:1856
	s_waitcnt vmcnt(30)
	v_mfma_f32_16x16x32_bf16 v[4:7], v[192:195], v[200:203], v[4:7]
	v_mfma_f32_16x16x32_bf16 v[0:3], v[196:199], v[200:203], v[0:3]
	global_load_dwordx4 v[192:195], v[62:63], off offset:1920
	global_load_dwordx4 v[196:199], v[64:65], off offset:1920
	global_load_dwordx4 v[200:203], v[66:67], off offset:1920
	s_waitcnt vmcnt(30)
	v_mfma_f32_16x16x32_bf16 v[4:7], v[216:219], v[224:227], v[4:7]
	v_mfma_f32_16x16x32_bf16 v[0:3], v[220:223], v[224:227], v[0:3]
	global_load_dwordx4 v[216:219], v[62:63], off offset:1984
	global_load_dwordx4 v[220:223], v[64:65], off offset:1984
	global_load_dwordx4 v[224:227], v[66:67], off offset:1984
	s_waitcnt vmcnt(30)
	v_mfma_f32_16x16x32_bf16 v[4:7], v[228:231], v[236:239], v[4:7]
	v_mfma_f32_16x16x32_bf16 v[0:3], v[232:235], v[236:239], v[0:3]
	global_load_dwordx4 v[228:231], v[62:63], off offset:2048
	global_load_dwordx4 v[232:235], v[64:65], off offset:2048
	global_load_dwordx4 v[236:239], v[66:67], off offset:2048
	s_waitcnt vmcnt(30)
	v_mfma_f32_16x16x32_bf16 v[4:7], v[72:75], v[80:83], v[4:7]
	v_mfma_f32_16x16x32_bf16 v[0:3], v[76:79], v[80:83], v[0:3]
	global_load_dwordx4 v[72:75], v[62:63], off offset:2112
	global_load_dwordx4 v[76:79], v[64:65], off offset:2112
	global_load_dwordx4 v[80:83], v[66:67], off offset:2112
	s_waitcnt vmcnt(30)
	v_mfma_f32_16x16x32_bf16 v[4:7], v[84:87], v[92:95], v[4:7]
	v_mfma_f32_16x16x32_bf16 v[0:3], v[88:91], v[92:95], v[0:3]
	global_load_dwordx4 v[84:87], v[62:63], off offset:2176
	global_load_dwordx4 v[88:91], v[64:65], off offset:2176
	global_load_dwordx4 v[92:95], v[66:67], off offset:2176
	s_waitcnt vmcnt(30)
	v_mfma_f32_16x16x32_bf16 v[4:7], v[96:99], v[104:107], v[4:7]
	v_mfma_f32_16x16x32_bf16 v[0:3], v[100:103], v[104:107], v[0:3]
	global_load_dwordx4 v[96:99], v[62:63], off offset:2240
	global_load_dwordx4 v[100:103], v[64:65], off offset:2240
	global_load_dwordx4 v[104:107], v[66:67], off offset:2240
	s_waitcnt vmcnt(30)
	v_mfma_f32_16x16x32_bf16 v[4:7], v[108:111], v[116:119], v[4:7]
	v_mfma_f32_16x16x32_bf16 v[0:3], v[112:115], v[116:119], v[0:3]
	global_load_dwordx4 v[108:111], v[62:63], off offset:2304
	global_load_dwordx4 v[112:115], v[64:65], off offset:2304
	global_load_dwordx4 v[116:119], v[66:67], off offset:2304
	s_waitcnt vmcnt(30)
; template <int MODE>
; __device__ __forceinline__ void sample_gemm(const Params& p, int l, const int tid) {
;     ...
;         for (int hh = 0; hh < 2; ++hh) {
; #pragma unroll 8
;             for (int k = hh * 1024; k < hh * 1024 + 1024; k += 32) {
;                 const bf16x8 fa0 = *(const bf16x8*)(a0 + k), fa1 = *(const bf16x8*)(a1 + k), fb = *(const bf16x8*)(bp + k);
;                 const int ci = (MODE == 2) ? hh : 0;
;                 c[ci][0] = __builtin_amdgcn_mfma_f32_16x16x32_bf16(fa0, fb, c[ci][0], 0, 0, 0);
;                 c[ci][1] = __builtin_amdgcn_mfma_f32_16x16x32_bf16(fa1, fb, c[ci][1], 0, 0, 0);
;             }
	v_mfma_f32_16x16x32_bf16 v[4:7], v[120:123], v[128:131], v[4:7]
	v_mfma_f32_16x16x32_bf16 v[0:3], v[124:127], v[128:131], v[0:3]
	global_load_dwordx4 v[120:123], v[62:63], off offset:2368
	global_load_dwordx4 v[124:127], v[64:65], off offset:2368
	global_load_dwordx4 v[128:131], v[66:67], off offset:2368
	s_waitcnt vmcnt(30)
	v_mfma_f32_16x16x32_bf16 v[4:7], v[140:143], v[148:151], v[4:7]
	v_mfma_f32_16x16x32_bf16 v[0:3], v[144:147], v[148:151], v[0:3]
	global_load_dwordx4 v[140:143], v[62:63], off offset:2432
	global_load_dwordx4 v[144:147], v[64:65], off offset:2432
	global_load_dwordx4 v[148:151], v[66:67], off offset:2432
	s_waitcnt vmcnt(30)
	v_mfma_f32_16x16x32_bf16 v[4:7], v[152:155], v[160:163], v[4:7]
	v_mfma_f32_16x16x32_bf16 v[0:3], v[156:159], v[160:163], v[0:3]
	global_load_dwordx4 v[152:155], v[62:63], off offset:2496
	global_load_dwordx4 v[156:159], v[64:65], off offset:2496
	global_load_dwordx4 v[160:163], v[66:67], off offset:2496
	s_waitcnt vmcnt(30)
	v_mfma_f32_16x16x32_bf16 v[4:7], v[164:167], v[172:175], v[4:7]
	v_mfma_f32_16x16x32_bf16 v[0:3], v[168:171], v[172:175], v[0:3]
	global_load_dwordx4 v[164:167], v[62:63], off offset:2560
	global_load_dwordx4 v[168:171], v[64:65], off offset:2560
	global_load_dwordx4 v[172:175], v[66:67], off offset:2560
	s_waitcnt vmcnt(30)
	v_mfma_f32_16x16x32_bf16 v[4:7], v[192:195], v[200:203], v[4:7]
	v_mfma_f32_16x16x32_bf16 v[0:3], v[196:199], v[200:203], v[0:3]
	global_load_dwordx4 v[192:195], v[62:63], off offset:2624
	global_load_dwordx4 v[196:199], v[64:65], off offset:2624
	global_load_dwordx4 v[200:203], v[66:67], off offset:2624
	s_waitcnt vmcnt(30)
	v_mfma_f32_16x16x32_bf16 v[4:7], v[216:219], v[224:227], v[4:7]
	v_mfma_f32_16x16x32_bf16 v[0:3], v[220:223], v[224:227], v[0:3]
	global_load_dwordx4 v[216:219], v[62:63], off offset:2688
	global_load_dwordx4 v[220:223], v[64:65], off offset:2688
	global_load_dwordx4 v[224:227], v[66:67], off offset:2688
	s_waitcnt vmcnt(30)
	v_mfma_f32_16x16x32_bf16 v[4:7], v[228:231], v[236:239], v[4:7]
	v_mfma_f32_16x16x32_bf16 v[0:3], v[232:235], v[236:239], v[0:3]
	global_load_dwordx4 v[228:231], v[62:63], off offset:2752
	global_load_dwordx4 v[232:235], v[64:65], off offset:2752
	global_load_dwordx4 v[236:239], v[66:67], off offset:2752
	s_waitcnt vmcnt(30)
	v_mfma_f32_16x16x32_bf16 v[4:7], v[72:75], v[80:83], v[4:7]
	v_mfma_f32_16x16x32_bf16 v[0:3], v[76:79], v[80:83], v[0:3]
	global_load_dwordx4 v[72:75], v[62:63], off offset:2816
	global_load_dwordx4 v[76:79], v[64:65], off offset:2816
	global_load_dwordx4 v[80:83], v[66:67], off offset:2816
	s_waitcnt vmcnt(30)
	v_mfma_f32_16x16x32_bf16 v[4:7], v[84:87], v[92:95], v[4:7]
	v_mfma_f32_16x16x32_bf16 v[0:3], v[88:91], v[92:95], v[0:3]
	global_load_dwordx4 v[84:87], v[62:63], off offset:2880
	global_load_dwordx4 v[88:91], v[64:65], off offset:2880
	global_load_dwordx4 v[92:95], v[66:67], off offset:2880
	s_waitcnt vmcnt(30)
	v_mfma_f32_16x16x32_bf16 v[4:7], v[96:99], v[104:107], v[4:7]
	v_mfma_f32_16x16x32_bf16 v[0:3], v[100:103], v[104:107], v[0:3]
	global_load_dwordx4 v[96:99], v[62:63], off offset:2944
	global_load_dwordx4 v[100:103], v[64:65], off offset:2944
	global_load_dwordx4 v[104:107], v[66:67], off offset:2944
	s_waitcnt vmcnt(30)
	v_mfma_f32_16x16x32_bf16 v[4:7], v[108:111], v[116:119], v[4:7]
	v_mfma_f32_16x16x32_bf16 v[0:3], v[112:115], v[116:119], v[0:3]
	global_load_dwordx4 v[108:111], v[62:63], off offset:3008
	global_load_dwordx4 v[112:115], v[64:65], off offset:3008
	global_load_dwordx4 v[116:119], v[66:67], off offset:3008
	s_waitcnt vmcnt(30)
	v_mfma_f32_16x16x32_bf16 v[4:7], v[120:123], v[128:131], v[4:7]
	v_mfma_f32_16x16x32_bf16 v[0:3], v[124:127], v[128:131], v[0:3]
	global_load_dwordx4 v[120:123], v[62:63], off offset:3072
	global_load_dwordx4 v[124:127], v[64:65], off offset:3072
	global_load_dwordx4 v[128:131], v[66:67], off offset:3072
	s_waitcnt vmcnt(30)
	v_mfma_f32_16x16x32_bf16 v[4:7], v[140:143], v[148:151], v[4:7]
	v_mfma_f32_16x16x32_bf16 v[0:3], v[144:147], v[148:151], v[0:3]
	global_load_dwordx4 v[140:143], v[62:63], off offset:3136
	global_load_dwordx4 v[144:147], v[64:65], off offset:3136
	global_load_dwordx4 v[148:151], v[66:67], off offset:3136
	s_waitcnt vmcnt(30)
	v_mfma_f32_16x16x32_bf16 v[4:7], v[152:155], v[160:163], v[4:7]
	v_mfma_f32_16x16x32_bf16 v[0:3], v[156:159], v[160:163], v[0:3]
	global_load_dwordx4 v[152:155], v[62:63], off offset:3200
	global_load_dwordx4 v[156:159], v[64:65], off offset:3200
	global_load_dwordx4 v[160:163], v[66:67], off offset:3200
	s_waitcnt vmcnt(30)
	v_mfma_f32_16x16x32_bf16 v[4:7], v[164:167], v[172:175], v[4:7]
	v_mfma_f32_16x16x32_bf16 v[0:3], v[168:171], v[172:175], v[0:3]
	global_load_dwordx4 v[164:167], v[62:63], off offset:3264
	global_load_dwordx4 v[168:171], v[64:65], off offset:3264
	global_load_dwordx4 v[172:175], v[66:67], off offset:3264
	s_waitcnt vmcnt(30)
	v_mfma_f32_16x16x32_bf16 v[4:7], v[192:195], v[200:203], v[4:7]
	v_mfma_f32_16x16x32_bf16 v[0:3], v[196:199], v[200:203], v[0:3]
	global_load_dwordx4 v[192:195], v[62:63], off offset:3328
	global_load_dwordx4 v[196:199], v[64:65], off offset:3328
	global_load_dwordx4 v[200:203], v[66:67], off offset:3328
	s_waitcnt vmcnt(30)
	v_mfma_f32_16x16x32_bf16 v[4:7], v[216:219], v[224:227], v[4:7]
	v_mfma_f32_16x16x32_bf16 v[0:3], v[220:223], v[224:227], v[0:3]
	global_load_dwordx4 v[216:219], v[62:63], off offset:3392
	global_load_dwordx4 v[220:223], v[64:65], off offset:3392
	global_load_dwordx4 v[224:227], v[66:67], off offset:3392
	s_waitcnt vmcnt(30)
; template <int MODE>
; __device__ __forceinline__ void sample_gemm(const Params& p, int l, const int tid) {
;     ...
;         for (int hh = 0; hh < 2; ++hh) {
; #pragma unroll 8
;             for (int k = hh * 1024; k < hh * 1024 + 1024; k += 32) {
;                 const bf16x8 fa0 = *(const bf16x8*)(a0 + k), fa1 = *(const bf16x8*)(a1 + k), fb = *(const bf16x8*)(bp + k);
;                 const int ci = (MODE == 2) ? hh : 0;
;                 c[ci][0] = __builtin_amdgcn_mfma_f32_16x16x32_bf16(fa0, fb, c[ci][0], 0, 0, 0);
;                 c[ci][1] = __builtin_amdgcn_mfma_f32_16x16x32_bf16(fa1, fb, c[ci][1], 0, 0, 0);
;             }
	v_mfma_f32_16x16x32_bf16 v[4:7], v[228:231], v[236:239], v[4:7]
	v_mfma_f32_16x16x32_bf16 v[0:3], v[232:235], v[236:239], v[0:3]
	global_load_dwordx4 v[228:231], v[62:63], off offset:3456
	global_load_dwordx4 v[232:235], v[64:65], off offset:3456
	global_load_dwordx4 v[236:239], v[66:67], off offset:3456
	s_waitcnt vmcnt(30)
	v_mfma_f32_16x16x32_bf16 v[4:7], v[72:75], v[80:83], v[4:7]
	v_mfma_f32_16x16x32_bf16 v[0:3], v[76:79], v[80:83], v[0:3]
	global_load_dwordx4 v[72:75], v[62:63], off offset:3520
	global_load_dwordx4 v[76:79], v[64:65], off offset:3520
	global_load_dwordx4 v[80:83], v[66:67], off offset:3520
	s_waitcnt vmcnt(30)
	v_mfma_f32_16x16x32_bf16 v[4:7], v[84:87], v[92:95], v[4:7]
	v_mfma_f32_16x16x32_bf16 v[0:3], v[88:91], v[92:95], v[0:3]
	global_load_dwordx4 v[84:87], v[62:63], off offset:3584
	global_load_dwordx4 v[88:91], v[64:65], off offset:3584
	global_load_dwordx4 v[92:95], v[66:67], off offset:3584
	s_waitcnt vmcnt(30)
	v_mfma_f32_16x16x32_bf16 v[4:7], v[96:99], v[104:107], v[4:7]
	v_mfma_f32_16x16x32_bf16 v[0:3], v[100:103], v[104:107], v[0:3]
	global_load_dwordx4 v[96:99], v[62:63], off offset:3648
	global_load_dwordx4 v[100:103], v[64:65], off offset:3648
	global_load_dwordx4 v[104:107], v[66:67], off offset:3648
	s_waitcnt vmcnt(30)
	v_mfma_f32_16x16x32_bf16 v[4:7], v[108:111], v[116:119], v[4:7]
	v_mfma_f32_16x16x32_bf16 v[0:3], v[112:115], v[116:119], v[0:3]
	global_load_dwordx4 v[108:111], v[62:63], off offset:3712
	global_load_dwordx4 v[112:115], v[64:65], off offset:3712
	global_load_dwordx4 v[116:119], v[66:67], off offset:3712
	s_waitcnt vmcnt(30)
	v_mfma_f32_16x16x32_bf16 v[4:7], v[120:123], v[128:131], v[4:7]
	v_mfma_f32_16x16x32_bf16 v[0:3], v[124:127], v[128:131], v[0:3]
	global_load_dwordx4 v[120:123], v[62:63], off offset:3776
	global_load_dwordx4 v[124:127], v[64:65], off offset:3776
	global_load_dwordx4 v[128:131], v[66:67], off offset:3776
	s_waitcnt vmcnt(30)
	v_mfma_f32_16x16x32_bf16 v[4:7], v[140:143], v[148:151], v[4:7]
	v_mfma_f32_16x16x32_bf16 v[0:3], v[144:147], v[148:151], v[0:3]
	global_load_dwordx4 v[140:143], v[62:63], off offset:3840
	global_load_dwordx4 v[144:147], v[64:65], off offset:3840
	global_load_dwordx4 v[148:151], v[66:67], off offset:3840
	s_waitcnt vmcnt(30)
	v_mfma_f32_16x16x32_bf16 v[4:7], v[152:155], v[160:163], v[4:7]
	v_mfma_f32_16x16x32_bf16 v[0:3], v[156:159], v[160:163], v[0:3]
	global_load_dwordx4 v[152:155], v[62:63], off offset:3904
	global_load_dwordx4 v[156:159], v[64:65], off offset:3904
	global_load_dwordx4 v[160:163], v[66:67], off offset:3904
	s_waitcnt vmcnt(30)
	v_mfma_f32_16x16x32_bf16 v[4:7], v[164:167], v[172:175], v[4:7]
	v_mfma_f32_16x16x32_bf16 v[0:3], v[168:171], v[172:175], v[0:3]
	global_load_dwordx4 v[164:167], v[62:63], off offset:3968
	global_load_dwordx4 v[168:171], v[64:65], off offset:3968
	global_load_dwordx4 v[172:175], v[66:67], off offset:3968
	s_waitcnt vmcnt(30)
	v_mfma_f32_16x16x32_bf16 v[4:7], v[192:195], v[200:203], v[4:7]
	v_mfma_f32_16x16x32_bf16 v[0:3], v[196:199], v[200:203], v[0:3]
	global_load_dwordx4 v[192:195], v[62:63], off offset:4032
	global_load_dwordx4 v[196:199], v[64:65], off offset:4032
	global_load_dwordx4 v[200:203], v[66:67], off offset:4032
	s_waitcnt vmcnt(30)
	v_mfma_f32_16x16x32_bf16 v[4:7], v[216:219], v[224:227], v[4:7]
	v_mfma_f32_16x16x32_bf16 v[0:3], v[220:223], v[224:227], v[0:3]
	s_waitcnt vmcnt(27)
	v_mfma_f32_16x16x32_bf16 v[4:7], v[228:231], v[236:239], v[4:7]
	v_mfma_f32_16x16x32_bf16 v[0:3], v[232:235], v[236:239], v[0:3]
	s_waitcnt vmcnt(24)
	v_mfma_f32_16x16x32_bf16 v[4:7], v[72:75], v[80:83], v[4:7]
	v_mfma_f32_16x16x32_bf16 v[0:3], v[76:79], v[80:83], v[0:3]
	s_waitcnt vmcnt(21)
; __device__ __forceinline__ float bf2f(bf16_t v) { return __uint_as_float(((unsigned)v) << 16); }
; __device__ __forceinline__ bf16_t f2bf(float f) { return (bf16_t)(pk2(f, 0.f) & 0xffffu); }
; template <int MODE>
; __device__ __forceinline__ void sample_gemm(const Params& p, int l, const int tid) {
;     ...
;             for (int k = hh * 1024; k < hh * 1024 + 1024; k += 32) {
;                 const bf16x8 fa0 = *(const bf16x8*)(a0 + k), fa1 = *(const bf16x8*)(a1 + k), fb = *(const bf16x8*)(bp + k);
;                 const int ci = (MODE == 2) ? hh : 0;
;                 c[ci][0] = __builtin_amdgcn_mfma_f32_16x16x32_bf16(fa0, fb, c[ci][0], 0, 0, 0);
;                 c[ci][1] = __builtin_amdgcn_mfma_f32_16x16x32_bf16(fa1, fb, c[ci][1], 0, 0, 0);
;             }
;     ...
;         const int col = n0 + r16;
; #pragma unroll
;         for (int i = 0; i < 2; ++i)
; #pragma unroll
;             for (int j = 0; j < 4; ++j) {
;                 const int row = MP + wid * 32 + i * 16 + quad * 4 + j;
;                 if (MODE == 2) {
;                     const float sa = bf2f(((const bf16_t*)(p.ws + WS_MA))[(size_t)row * 2048 + col]), sb = bf2f(((const bf16_t*)(p.ws + WS_MB))[(size_t)row * 2048 + col]);
;                     ((bf16_t*)(p.ws + WS_MERGED))[(size_t)row * 2048 + col] = f2bf(sa * c[0][i][j] + sb * c[1][i][j]);
;                 } else {
;                     const float g = ((const float*)(p.ws + WS_MOD))[((size_t)l * 16 + batch_of(row)) * 6144 + 4096 + col];
;                     p.out[(size_t)row * DM + col] = xrow(p, l, row)[col] + g * c[0][i][j];
;                 }
	v_mfma_f32_16x16x32_bf16 v[4:7], v[84:87], v[92:95], v[4:7]
	v_mfma_f32_16x16x32_bf16 v[0:3], v[88:91], v[92:95], v[0:3]
	s_waitcnt vmcnt(18)
	v_mfma_f32_16x16x32_bf16 v[4:7], v[96:99], v[104:107], v[4:7]
	v_mfma_f32_16x16x32_bf16 v[0:3], v[100:103], v[104:107], v[0:3]
	s_waitcnt vmcnt(15)
	v_mfma_f32_16x16x32_bf16 v[4:7], v[108:111], v[116:119], v[4:7]
	v_mfma_f32_16x16x32_bf16 v[0:3], v[112:115], v[116:119], v[0:3]
	s_waitcnt vmcnt(12)
	v_mfma_f32_16x16x32_bf16 v[4:7], v[120:123], v[128:131], v[4:7]
	v_mfma_f32_16x16x32_bf16 v[0:3], v[124:127], v[128:131], v[0:3]
	s_waitcnt vmcnt(9)
	v_mfma_f32_16x16x32_bf16 v[4:7], v[140:143], v[148:151], v[4:7]
	v_mfma_f32_16x16x32_bf16 v[0:3], v[144:147], v[148:151], v[0:3]
	s_waitcnt vmcnt(6)
	v_mfma_f32_16x16x32_bf16 v[4:7], v[152:155], v[160:163], v[4:7]
	v_mfma_f32_16x16x32_bf16 v[0:3], v[156:159], v[160:163], v[0:3]
	s_waitcnt vmcnt(3)
	v_mfma_f32_16x16x32_bf16 v[4:7], v[164:167], v[172:175], v[4:7]
	v_mfma_f32_16x16x32_bf16 v[0:3], v[168:171], v[172:175], v[0:3]
	s_waitcnt vmcnt(0)
	v_mfma_f32_16x16x32_bf16 v[4:7], v[192:195], v[200:203], v[4:7]
	v_mfma_f32_16x16x32_bf16 v[0:3], v[196:199], v[200:203], v[0:3]
	v_lshl_or_b32 v60, s4, 4, v71
	v_ashrrev_i32_e32 v61, 31, v60
	v_lshlrev_b64 v[62:63], 2, v[60:61]
	v_lshl_add_u64 v[64:65], s[2:3], 0, v[62:63]
	v_lshl_add_u64 v[60:61], s[90:91], 0, v[62:63]
	v_lshl_add_u64 v[66:67], v[64:65], 0, v[8:9]
	global_load_dword v72, v[66:67], off
	v_lshl_add_u64 v[66:67], v[24:25], 0, v[62:63]
	global_load_dword v84, v[66:67], off
	v_lshl_add_u64 v[66:67], v[64:65], 0, v[10:11]
	global_load_dword v73, v[66:67], off
	v_lshl_add_u64 v[66:67], v[28:29], 0, v[62:63]
	global_load_dword v85, v[66:67], off
	v_lshl_add_u64 v[66:67], v[64:65], 0, v[12:13]
	global_load_dword v74, v[66:67], off
	v_lshl_add_u64 v[66:67], v[32:33], 0, v[62:63]
	global_load_dword v86, v[66:67], off
	v_lshl_add_u64 v[66:67], v[64:65], 0, v[14:15]
	global_load_dword v75, v[66:67], off
	v_lshl_add_u64 v[66:67], v[36:37], 0, v[62:63]
	global_load_dword v87, v[66:67], off
	v_lshl_add_u64 v[66:67], v[64:65], 0, v[16:17]
	global_load_dword v76, v[66:67], off
	v_lshl_add_u64 v[66:67], v[40:41], 0, v[62:63]
	global_load_dword v88, v[66:67], off
	v_lshl_add_u64 v[66:67], v[64:65], 0, v[18:19]
	global_load_dword v77, v[66:67], off
	v_lshl_add_u64 v[66:67], v[44:45], 0, v[62:63]
	global_load_dword v89, v[66:67], off
	v_lshl_add_u64 v[66:67], v[64:65], 0, v[20:21]
	global_load_dword v78, v[66:67], off
	v_lshl_add_u64 v[66:67], v[48:49], 0, v[62:63]
	global_load_dword v90, v[66:67], off
	v_lshl_add_u64 v[66:67], v[64:65], 0, v[22:23]
	global_load_dword v79, v[66:67], off
	v_lshl_add_u64 v[66:67], v[52:53], 0, v[62:63]
	global_load_dword v91, v[66:67], off
	s_add_i32 s4, s4, s80
	v_add_u32_e32 v58, s1, v58
	s_waitcnt vmcnt(0)
	v_fmac_f32_e32 v84, v4, v72
	v_lshl_add_u64 v[66:67], v[60:61], 0, v[26:27]
	global_store_dword v[66:67], v84, off
	v_fmac_f32_e32 v85, v5, v73
	v_lshl_add_u64 v[66:67], v[60:61], 0, v[30:31]
	global_store_dword v[66:67], v85, off
	v_fmac_f32_e32 v86, v6, v74
	v_lshl_add_u64 v[66:67], v[60:61], 0, v[34:35]
	global_store_dword v[66:67], v86, off
	v_fmac_f32_e32 v87, v7, v75
	v_lshl_add_u64 v[66:67], v[60:61], 0, v[38:39]
	global_store_dword v[66:67], v87, off
	v_fmac_f32_e32 v88, v0, v76
	v_lshl_add_u64 v[66:67], v[60:61], 0, v[42:43]
	global_store_dword v[66:67], v88, off
	v_fmac_f32_e32 v89, v1, v77
	v_lshl_add_u64 v[66:67], v[60:61], 0, v[46:47]
	global_store_dword v[66:67], v89, off
	v_fmac_f32_e32 v90, v2, v78
	v_lshl_add_u64 v[66:67], v[60:61], 0, v[50:51]
	global_store_dword v[66:67], v90, off
	v_fmac_f32_e32 v91, v3, v79
	v_lshl_add_u64 v[66:67], v[60:61], 0, v[54:55]
	global_store_dword v[66:67], v91, off
	s_cmpk_gt_i32 s4, 0x7f
	s_cbranch_scc0 .LBB0_709
